# hoisted residual loads in FFN2-down epilogue; attention row-blocks remapped to balance the two waves of each SIMD
# speedup vs baseline: 1.0483x; 1.0034x over previous
; __device__ __forceinline__ void attn_phase(const Params& p, LAS unsigned char* lds, int G) {
;     ...
;     float negsb;
;     {
;         float gq = fmaxf(fabsf(p.in[15][lane]), fabsf(p.in[15][64 + l32])), gk = fmaxf(fabsf(p.in[16][lane]), fabsf(p.in[16][64 + l32]));
; #pragma unroll
;         for (int o = 1; o < 64; o <<= 1) { gq = fmaxf(gq, __shfl_xor(gq, o)); gk = fmaxf(gk, __shfl_xor(gk, o)); }
;         negsb = -(96.f * gq * gk * QSCALE);
;     }
;     f32x16 negv;
; #pragma unroll
;     for (int e = 0; e < 16; ++e) negv[e] = negsb;
;     asm volatile("" : "+v"(negv));
.LBB0_628:
	s_cmp_lt_i32 s94, 7
	s_cselect_b64 s[4:5], -1, 0
	s_and_b64 s[28:29], s[4:5], s[0:1]
	s_andn2_b64 vcc, exec, s[28:29]
	s_cbranch_vccnz .LBB0_660
	s_waitcnt vmcnt(0)
	v_mov_b32_e32 v16, v166
	v_mbcnt_lo_u32_b32 v4, -1, 0
	v_and_b32_e32 v17, 63, v16
	v_and_b32_e32 v170, 31, v16
	v_lshlrev_b32_e32 v0, 2, v17
	v_lshlrev_b32_e32 v171, 2, v170
	s_waitcnt lgkmcnt(0)
	global_load_dword v1, v171, s[70:71] offset:256
	global_load_dword v2, v0, s[70:71]
	global_load_dword v3, v171, s[72:73] offset:256
	s_nop 0
	global_load_dword v0, v0, s[72:73]
	v_mbcnt_hi_u32_b32 v4, -1, v4
	v_and_b32_e32 v5, 64, v4
	v_xor_b32_e32 v6, 1, v4
	v_add_u32_e32 v5, 64, v5
	v_cmp_lt_i32_e32 vcc, v6, v5
	v_xor_b32_e32 v7, 2, v4
	v_xor_b32_e32 v8, 4, v4
	v_cndmask_b32_e32 v6, v4, v6, vcc
	v_lshlrev_b32_e32 v167, 2, v6
	v_cmp_lt_i32_e32 vcc, v7, v5
	v_xor_b32_e32 v9, 8, v4
	v_xor_b32_e32 v10, 16, v4
	v_cndmask_b32_e32 v6, v4, v7, vcc
	v_lshlrev_b32_e32 v168, 2, v6
	v_cmp_lt_i32_e32 vcc, v8, v5
	v_xor_b32_e32 v11, 32, v4
	s_cmpk_gt_i32 s2, 0x7ff
	v_cndmask_b32_e32 v6, v4, v8, vcc
	v_lshlrev_b32_e32 v6, 2, v6
	v_cmp_lt_i32_e32 vcc, v9, v5
	s_mov_b32 s31, 0
	v_readfirstlane_b32 s0, v16
	s_waitcnt vmcnt(3)
	v_max_f32_e64 v1, |v1|, |v1|
	s_waitcnt vmcnt(2)
	v_max_f32_e64 v2, |v2|, |v2|
	s_waitcnt vmcnt(1)
	v_max_f32_e64 v3, |v3|, |v3|
	s_waitcnt vmcnt(0)
	v_max_f32_e64 v0, |v0|, |v0|
	v_max_f32_e32 v1, v2, v1
	v_max_f32_e32 v0, v0, v3
	ds_bpermute_b32 v2, v167, v1
	ds_bpermute_b32 v3, v167, v0
	s_waitcnt lgkmcnt(1)
	v_max_f32_e32 v2, v2, v2
	s_waitcnt lgkmcnt(0)
	v_max_f32_e32 v3, v3, v3
	v_max_f32_e32 v1, v1, v2
	v_max_f32_e32 v0, v0, v3
	ds_bpermute_b32 v2, v168, v1
	ds_bpermute_b32 v3, v168, v0
	s_waitcnt lgkmcnt(1)
	v_max_f32_e32 v2, v2, v2
	s_waitcnt lgkmcnt(0)
	v_max_f32_e32 v3, v3, v3
	v_max_f32_e32 v1, v1, v2
	v_max_f32_e32 v0, v0, v3
	ds_bpermute_b32 v2, v6, v1
	ds_bpermute_b32 v3, v6, v0
	v_cndmask_b32_e32 v6, v4, v9, vcc
	v_lshlrev_b32_e32 v6, 2, v6
	v_cmp_lt_i32_e32 vcc, v10, v5
	s_waitcnt lgkmcnt(1)
	v_max_f32_e32 v2, v2, v2
	s_waitcnt lgkmcnt(0)
	v_max_f32_e32 v3, v3, v3
	v_max_f32_e32 v1, v1, v2
	v_max_f32_e32 v0, v0, v3
	ds_bpermute_b32 v2, v6, v1
	ds_bpermute_b32 v3, v6, v0
	v_cndmask_b32_e32 v6, v4, v10, vcc
	v_lshlrev_b32_e32 v6, 2, v6
	v_cmp_lt_i32_e32 vcc, v11, v5
	s_waitcnt lgkmcnt(1)
	v_max_f32_e32 v2, v2, v2
	s_waitcnt lgkmcnt(0)
	v_max_f32_e32 v3, v3, v3
	v_max_f32_e32 v1, v1, v2
	v_max_f32_e32 v0, v0, v3
	ds_bpermute_b32 v2, v6, v1
	ds_bpermute_b32 v3, v6, v0
	v_cndmask_b32_e32 v4, v4, v11, vcc
	v_lshlrev_b32_e32 v169, 2, v4
	s_waitcnt lgkmcnt(1)
	v_max_f32_e32 v2, v2, v2
	s_waitcnt lgkmcnt(0)
	v_max_f32_e32 v3, v3, v3
	v_max_f32_e32 v1, v1, v2
	v_max_f32_e32 v0, v0, v3
	ds_bpermute_b32 v2, v169, v1
	ds_bpermute_b32 v3, v169, v0
	s_waitcnt lgkmcnt(1)
	v_max_f32_e32 v2, v2, v2
	s_waitcnt lgkmcnt(0)
	v_max_f32_e32 v3, v3, v3
	v_max_f32_e32 v1, v1, v2
	v_max_f32_e32 v0, v0, v3
	v_mul_f32_e32 v1, 0x42c00000, v1
	v_mul_f32_e32 v0, v0, v1
	v_mul_f32_e32 v0, 0xbe16c740, v0
	v_mov_b32_e32 v1, v0
	v_mov_b32_e32 v2, v0
	v_mov_b32_e32 v3, v0
	v_mov_b32_e32 v4, v0
	v_mov_b32_e32 v5, v0
	v_mov_b32_e32 v6, v0
	v_mov_b32_e32 v7, v0
	v_mov_b32_e32 v8, v0
	v_mov_b32_e32 v9, v0
	v_mov_b32_e32 v10, v0
	v_mov_b32_e32 v11, v0
	v_mov_b32_e32 v12, v0
	v_mov_b32_e32 v13, v0
	v_mov_b32_e32 v14, v0
	v_mov_b32_e32 v15, v0
	s_cbranch_scc1 .LBB0_649
; __device__ __forceinline__ void attn_phase(const Params& p, LAS unsigned char* lds, int G) {
;     ...
;     const int kr0 = tid / 12, kc0 = tid - kr0 * 12;
;     const int kr1 = (tid + 512) / 12, kc1 = (tid + 512) - kr1 * 12;
;     const int kr2 = (tid + 1024) / 12, kc2 = (tid + 1024) - kr2 * 12;
;     const int vr0 = tid >> 4, vc0 = tid & 15;
;     float negsb;
;     {
;         float gq = fmaxf(fabsf(p.in[15][lane]), fabsf(p.in[15][64 + l32])), gk = fmaxf(fabsf(p.in[16][lane]), fabsf(p.in[16][64 + l32]));
; #pragma unroll
;         for (int o = 1; o < 64; o <<= 1) { gq = fmaxf(gq, __shfl_xor(gq, o)); gk = fmaxf(gk, __shfl_xor(gk, o)); }
;         negsb = -(96.f * gq * gk * QSCALE);
;     }
;     f32x16 negv;
; #pragma unroll
;     for (int e = 0; e < 16; ++e) negv[e] = negsb;
;     asm volatile("" : "+v"(negv));
;     for (int it = blockIdx.x; it < 2048; it += G) {
;         const int kk = it >> 8, cc = it & 255, bh = cc >> 1, set = cc & 1;
;         const int qt = set ? (14 - 2 * kk + (kk & 1)) : (15 - 2 * kk - (kk & 1));
;         const int q0 = qt * 256 + 32 * wave, lim = q0 >> 6, nkt = 4 * qt + 4;
	v_add_u32_e32 v18, 0x200, v16
	s_mov_b32 s1, 0x2aaaaaab
	v_mul_hi_i32 v19, v18, s1
	v_lshrrev_b32_e32 v20, 31, v19
	v_ashrrev_i32_e32 v19, 1, v19
	v_add_u32_e32 v30, v19, v20
	v_mad_u64_u32 v[18:19], s[10:11], v30, -12, v[18:19]
	v_add_u32_e32 v20, 0x400, v16
	v_mul_hi_i32 v19, v20, s1
	v_lshrrev_b32_e32 v21, 31, v19
	v_ashrrev_i32_e32 v19, 1, v19
	s_add_u32 s4, s92, 0x36000000
	v_add_u32_e32 v19, v19, v21
	s_addc_u32 s5, s93, 0
	v_mad_u64_u32 v[20:21], s[10:11], v19, -12, v[20:21]
	s_add_u32 s6, s92, 0x3c000000
	v_mul_hi_i32 v21, v16, s1
	s_addc_u32 s7, s93, 0
	v_lshrrev_b32_e32 v22, 31, v21
	v_ashrrev_i32_e32 v21, 1, v21
	s_add_u32 s34, s92, 0x22000000
	v_add_u32_e32 v31, v21, v22
	s_addc_u32 s35, s93, 0
	v_mad_u64_u32 v[22:23], s[10:11], v31, -12, v[16:17]
	s_add_u32 s8, s92, 0x3380000
	v_ashrrev_i32_e32 v24, 4, v16
	s_movk_i32 s11, 0x60
	s_addc_u32 s9, s93, 0
	s_ashr_i32 s10, s0, 1
	v_mad_i64_i32 v[126:127], s[0:1], v31, s11, 0
	v_mad_i64_i32 v[130:131], s[0:1], v30, s11, 0
	v_mad_i64_i32 v[134:135], s[0:1], v19, s11, 0
	v_ashrrev_i32_e32 v25, 31, v24
	v_mov_b32_e32 v125, 0
	v_lshlrev_b64 v[138:139], 12, v[24:25]
	s_mov_b64 s[0:1], 0x20000
	v_and_b32_e32 v124, 32, v17
	v_lshl_add_u64 v[140:141], v[138:139], 0, s[0:1]
	v_lshl_add_u64 v[28:29], s[92:93], 0, v[124:125]
	s_mov_b64 s[0:1], 0x2a00000
	v_lshl_add_u64 v[142:143], v[28:29], 0, s[0:1]
	s_mov_b64 s[0:1], 0x2e00000
	v_lshl_add_u64 v[144:145], v[28:29], 0, s[0:1]
	s_movk_i32 s0, 0x108
	v_lshrrev_b32_e32 v21, 5, v17
	v_lshlrev_b32_e32 v128, 3, v22
	v_mul_lo_u32 v23, v24, s0
	s_movk_i32 s0, 0xd0
	v_ashrrev_i32_e32 v129, 31, v128
	v_lshlrev_b32_e32 v132, 3, v18
	v_lshlrev_b32_e32 v136, 3, v20
	v_lshlrev_b32_e32 v26, 3, v21
	v_lshlrev_b32_e32 v176, 4, v18
	v_lshlrev_b32_e32 v178, 4, v20
	v_mad_u32_u24 v18, v170, s0, 0
	v_mul_u32_u24_e32 v20, 56, v170
	v_lshl_add_u32 v179, v21, 4, v18
	v_add3_u32 v180, v18, v20, v26
	v_lshlrev_b32_e32 v18, 2, v21
	v_lshlrev_b64 v[20:21], 1, v[128:129]
	s_movk_i32 s11, 0xc0
	v_mul_lo_u32 v173, v31, s0
	v_mul_lo_u32 v175, v30, s0
	v_mul_lo_u32 v177, v19, s0
	v_mad_i64_i32 v[20:21], s[0:1], v31, s11, v[20:21]
	v_ashrrev_i32_e32 v133, 31, v132
	v_lshl_add_u64 v[20:21], s[92:93], 0, v[20:21]
	s_mov_b64 s[0:1], 0x36006000
	v_lshl_add_u64 v[148:149], v[20:21], 0, s[0:1]
	v_lshlrev_b64 v[20:21], 1, v[132:133]
	v_mad_i64_i32 v[20:21], s[14:15], v30, s11, v[20:21]
	v_ashrrev_i32_e32 v137, 31, v136
	v_lshl_add_u64 v[20:21], s[92:93], 0, v[20:21]
	v_and_b32_e32 v27, 15, v16
	v_lshl_add_u64 v[150:151], v[20:21], 0, s[0:1]
	v_lshlrev_b64 v[20:21], 1, v[136:137]
	v_lshlrev_b32_e32 v24, 4, v27
	v_mad_i64_i32 v[20:21], s[14:15], v19, s11, v[20:21]
	v_lshlrev_b32_e32 v16, 3, v27
	v_add3_u32 v172, 0, v23, v24
	v_add_u32_e32 v23, 0, v173
	v_lshlrev_b32_e32 v174, 4, v22
	v_add_u32_e32 v22, 0, v175
	v_add_u32_e32 v24, 0, v177
	v_lshl_add_u64 v[20:21], s[92:93], 0, v[20:21]
	s_andn2_b32 s10, s10, 31
	v_add_u32_e32 v181, 0x3400, v179
	v_cmp_gt_u32_e64 s[38:39], 32, v17
	v_lshl_add_u64 v[146:147], s[70:71], 0, v[124:125]
	v_lshl_add_u64 v[152:153], v[20:21], 0, s[0:1]
	v_lshlrev_b32_e32 v124, 1, v16
	v_lshlrev_b32_e32 v154, 1, v26
	v_mov_b32_e32 v182, 0x358637bd
	v_mov_b32_e32 v183, 0x260
	s_mov_b32 s11, 0x3e16c740
	v_add_u32_e32 v184, v23, v174
	v_add_u32_e32 v185, v22, v176
	v_add_u32_e32 v186, v24, v178
	s_mov_b64 s[36:37], 0x6000
	v_lshlrev_b32_e32 v156, 1, v18
	v_mov_b32_e32 v187, 0xc0000
	v_mov_b32_e32 v188, 0x600
	s_mov_b32 s44, s2
	s_lshr_b32 s14, s10, 5
	s_lshl_b32 s15, s14, 1
	s_sub_u32 s16, 15, s15
	s_cmp_lt_u32 s14, 4
	s_cselect_b32 s14, s15, s16
	s_lshl_b32 s10, s14, 5
	v_and_b32_e32 v249, 31, v166
	v_mul_u32_u24_e32 v249, 0x110, v249
	v_bfe_u32 v251, v166, 5, 1
	v_lshl_add_u32 v249, v251, 4, v249
	v_bfe_u32 v250, v166, 4, 5
	v_mul_u32_u24_e32 v250, 0x110, v250
	v_bfe_u32 v251, v166, 1, 3
	v_lshl_add_u32 v250, v251, 5, v250
	v_and_b32_e32 v251, 1, v166
	v_lshl_add_u32 v250, v251, 3, v250
	v_cmp_gt_u32_e32 vcc, 96, v166
	s_nop 3
	s_and_saveexec_b64 s[0:1], vcc
	v_lshlrev_b32_e32 v251, 2, v166
	global_load_dword v252, v251, s[70:71]
	v_add_u32_e32 v251, 0x1f000, v251
	s_waitcnt vmcnt(0)
	ds_write_b32 v251, v252
	s_mov_b64 exec, s[0:1]
	s_waitcnt lgkmcnt(0)
	s_barrier
	s_branch .LBB0_632

; __device__ __forceinline__ float sq4(f32x4 a) { return (a.x * a.x + a.y * a.y) + (a.z * a.z + a.w * a.w); }
; __device__ __forceinline__ u32x4 pack8(f32x4 a, f32x4 b) { u32x4 o; o.x = cvt_pk(a.x, a.y); o.y = cvt_pk(a.z, a.w); o.z = cvt_pk(b.x, b.y); o.w = cvt_pk(b.z, b.w); return o; }
;     __device__ __forceinline__ void operator()(const f32x4 (&acc)[2][2][4][2], const pg8::Unit& u, int wr, int wc, int fr, int fq) const {
;     ...
; #pragma unroll
;         for (int ai = 0; ai < 2; ++ai)
; #pragma unroll
;             for (int m = 0; m < 4; ++m) {
;                 const int row = row0 + ai * 128 + m * 16; float ssq = 0.f;
; #pragma unroll
;                 for (int bj = 0; bj < 2; ++bj) {
;                     const size_t idx = (size_t)row * D + col0 + bj * 128;
;                     f32x4 r0, r1;
;                     if (RF32) { r0 = *(const f32x4*)(R + idx); r1 = *(const f32x4*)(R + idx + 4); }
;                     else { const u32x4 w = *(const u32x4*)(X + idx); r0 = (f32x4){bflo(w.x), bfhi(w.x), bflo(w.y), bfhi(w.y)}; r1 = (f32x4){bflo(w.z), bfhi(w.z), bflo(w.w), bfhi(w.w)}; }
;                     const f32x4 v0 = r0 + acc[ai][bj][m][0] * s, v1 = r1 + acc[ai][bj][m][1] * s;
;                     ssq += sq4(v0) + sq4(v1);
;                     *(u32x4*)(X + idx) = pack8(v0, v1);
;                 }
;                 row_stat_add(SS, row, ssq, fq);
;             }
.LBB0_908:
	v_lshl_add_u32 v146, s59, 8, v148
	v_ashrrev_i32_e32 v147, 31, v146
	v_lshl_or_b32 v144, s58, 8, v150
	v_lshlrev_b64 v[156:157], 11, v[146:147]
	v_ashrrev_i32_e32 v145, 31, v144
	v_lshl_add_u64 v[156:157], s[96:97], 0, v[156:157]
	v_lshl_add_u64 v[160:161], v[144:145], 1, v[156:157]
	global_load_dwordx4 v[156:159], v[160:161], off
	global_load_dwordx4 v[168:171], v[160:161], off offset:256
	s_mov_b64 vcc, 0x8000
	v_lshl_add_u64 v[162:163], v[160:161], 0, vcc
	global_load_dwordx4 v[172:175], v[162:163], off
	global_load_dwordx4 v[176:179], v[162:163], off offset:256
	s_mov_b64 vcc, 0x10000
	v_lshl_add_u64 v[162:163], v[160:161], 0, vcc
	global_load_dwordx4 v[180:183], v[162:163], off
	global_load_dwordx4 v[184:187], v[162:163], off offset:256
	s_mov_b64 vcc, 0x18000
	v_lshl_add_u64 v[162:163], v[160:161], 0, vcc
	global_load_dwordx4 v[188:191], v[162:163], off
	global_load_dwordx4 v[192:195], v[162:163], off offset:256
	s_mov_b64 vcc, 0x40000
	v_lshl_add_u64 v[162:163], v[160:161], 0, vcc
	global_load_dwordx4 v[196:199], v[162:163], off
	global_load_dwordx4 v[200:203], v[162:163], off offset:256
	s_mov_b64 vcc, 0x48000
	v_lshl_add_u64 v[162:163], v[160:161], 0, vcc
	global_load_dwordx4 v[204:207], v[162:163], off
	global_load_dwordx4 v[208:211], v[162:163], off offset:256
	s_mov_b64 vcc, 0x50000
	v_lshl_add_u64 v[162:163], v[160:161], 0, vcc
	global_load_dwordx4 v[212:215], v[162:163], off
	global_load_dwordx4 v[216:219], v[162:163], off offset:256
	s_mov_b64 vcc, 0x58000
	v_lshl_add_u64 v[162:163], v[160:161], 0, vcc
	global_load_dwordx4 v[220:223], v[162:163], off
	s_waitcnt vmcnt(0)
	v_lshlrev_b32_e32 v162, 16, v156
	v_and_b32_e32 v163, 0xffff0000, v156
	v_lshlrev_b32_e32 v156, 16, v157
	v_and_b32_e32 v157, 0xffff0000, v157
	v_lshlrev_b32_e32 v164, 16, v158
	v_and_b32_e32 v165, 0xffff0000, v158
	v_lshlrev_b32_e32 v158, 16, v159
	v_and_b32_e32 v159, 0xffff0000, v159
	v_pk_fma_f32 v[126:127], v[126:127], 0.5, v[156:157] op_sel_hi:[1,0,1]
	v_pk_fma_f32 v[124:125], v[124:125], 0.5, v[162:163] op_sel_hi:[1,0,1]
	v_pk_fma_f32 v[156:157], v[122:123], 0.5, v[158:159] op_sel_hi:[1,0,1]
	v_pk_fma_f32 v[122:123], v[120:121], 0.5, v[164:165] op_sel_hi:[1,0,1]
	v_mul_f32_e32 v120, v125, v125
	v_mul_f32_e32 v121, v127, v127
	v_fmac_f32_e32 v120, v124, v124
	v_fmac_f32_e32 v121, v126, v126
	v_add_f32_e32 v120, v120, v121
	v_mul_f32_e32 v121, v123, v123
	v_mul_f32_e32 v155, v157, v157
	v_fmac_f32_e32 v121, v122, v122
	v_fmac_f32_e32 v155, v156, v156
	v_add_f32_e32 v121, v121, v155
	v_add_f32_e32 v155, v120, v121
	v_cvt_pk_bf16_f32 v120, v124, v125
	v_cvt_pk_bf16_f32 v121, v126, v127
	v_cvt_pk_bf16_f32 v122, v122, v123
	v_cvt_pk_bf16_f32 v123, v156, v157
	global_store_dwordx4 v[160:161], v[120:123], off
	s_nop 1
	v_mov_b64_e32 v[120:121], v[168:169]
	v_mov_b64_e32 v[122:123], v[170:171]
	v_lshlrev_b32_e32 v124, 16, v120
	v_and_b32_e32 v125, 0xffff0000, v120
	v_lshlrev_b32_e32 v120, 16, v121
	v_and_b32_e32 v121, 0xffff0000, v121
	v_lshlrev_b32_e32 v126, 16, v122
	v_and_b32_e32 v127, 0xffff0000, v122
	v_lshlrev_b32_e32 v122, 16, v123
	v_and_b32_e32 v123, 0xffff0000, v123
	v_pk_fma_f32 v[118:119], v[118:119], 0.5, v[120:121] op_sel_hi:[1,0,1]
	v_pk_fma_f32 v[116:117], v[116:117], 0.5, v[124:125] op_sel_hi:[1,0,1]
	v_pk_fma_f32 v[120:121], v[114:115], 0.5, v[122:123] op_sel_hi:[1,0,1]
	v_pk_fma_f32 v[114:115], v[112:113], 0.5, v[126:127] op_sel_hi:[1,0,1]
	v_mul_f32_e32 v112, v117, v117
	v_mul_f32_e32 v113, v119, v119
	v_fmac_f32_e32 v112, v116, v116
	v_fmac_f32_e32 v113, v118, v118
	v_add_f32_e32 v112, v112, v113
	v_mul_f32_e32 v113, v115, v115
	v_mul_f32_e32 v122, v121, v121
	v_fmac_f32_e32 v113, v114, v114
	v_fmac_f32_e32 v122, v120, v120
	v_add_f32_e32 v113, v113, v122
	v_add_f32_e32 v112, v112, v113
	v_add_f32_e32 v122, v155, v112
	v_cvt_pk_bf16_f32 v112, v116, v117
	v_cvt_pk_bf16_f32 v113, v118, v119
	v_cvt_pk_bf16_f32 v114, v114, v115
	v_cvt_pk_bf16_f32 v115, v120, v121
	global_store_dwordx4 v[160:161], v[112:115], off offset:256
	s_nop 1
	v_and_b32_e32 v113, 64, v154
	v_xor_b32_e32 v112, 16, v154
	v_add_u32_e32 v113, 64, v113
	v_cmp_lt_i32_e32 vcc, v112, v113
	v_xor_b32_e32 v115, 32, v154
	s_nop 0
	v_cndmask_b32_e32 v112, v154, v112, vcc
	v_lshlrev_b32_e32 v114, 2, v112
	ds_bpermute_b32 v112, v114, v122
	v_cmp_lt_i32_e32 vcc, v115, v113
	s_waitcnt lgkmcnt(0)
	v_add_f32_e32 v112, v122, v112
	v_cndmask_b32_e32 v113, v154, v115, vcc
	v_lshlrev_b32_e32 v115, 2, v113
	ds_bpermute_b32 v113, v115, v112
	s_and_saveexec_b64 s[44:45], s[36:37]
	s_cbranch_execz .LBB0_910
	v_lshl_add_u64 v[116:117], v[146:147], 2, s[12:13]
	s_waitcnt lgkmcnt(0)
	v_add_f32_e32 v112, v112, v113
	global_atomic_add_f32 v[116:117], v112, off
; __device__ __forceinline__ float sq4(f32x4 a) { return (a.x * a.x + a.y * a.y) + (a.z * a.z + a.w * a.w); }
; __device__ __forceinline__ u32x4 pack8(f32x4 a, f32x4 b) { u32x4 o; o.x = cvt_pk(a.x, a.y); o.y = cvt_pk(a.z, a.w); o.z = cvt_pk(b.x, b.y); o.w = cvt_pk(b.z, b.w); return o; }
;     __device__ __forceinline__ void operator()(const f32x4 (&acc)[2][2][4][2], const pg8::Unit& u, int wr, int wc, int fr, int fq) const {
;     ...
; #pragma unroll
;         for (int ai = 0; ai < 2; ++ai)
; #pragma unroll
;             for (int m = 0; m < 4; ++m) {
;                 const int row = row0 + ai * 128 + m * 16; float ssq = 0.f;
; #pragma unroll
;                 for (int bj = 0; bj < 2; ++bj) {
;                     const size_t idx = (size_t)row * D + col0 + bj * 128;
;                     f32x4 r0, r1;
;                     if (RF32) { r0 = *(const f32x4*)(R + idx); r1 = *(const f32x4*)(R + idx + 4); }
;                     else { const u32x4 w = *(const u32x4*)(X + idx); r0 = (f32x4){bflo(w.x), bfhi(w.x), bflo(w.y), bfhi(w.y)}; r1 = (f32x4){bflo(w.z), bfhi(w.z), bflo(w.w), bfhi(w.w)}; }
;                     const f32x4 v0 = r0 + acc[ai][bj][m][0] * s, v1 = r1 + acc[ai][bj][m][1] * s;
;                     ssq += sq4(v0) + sq4(v1);
;                     *(u32x4*)(X + idx) = pack8(v0, v1);
;                 }
;                 row_stat_add(SS, row, ssq, fq);
;             }
.LBB0_910:
	s_or_b64 exec, exec, s[44:45]
	v_or_b32_e32 v112, 16, v146
	s_waitcnt lgkmcnt(0)
	v_ashrrev_i32_e32 v113, 31, v112
	v_lshlrev_b64 v[116:117], 11, v[112:113]
	v_lshl_add_u64 v[116:117], s[96:97], 0, v[116:117]
	v_lshl_add_u64 v[120:121], v[144:145], 1, v[116:117]
	s_nop 1
	v_mov_b64_e32 v[116:117], v[172:173]
	v_mov_b64_e32 v[118:119], v[174:175]
	v_lshlrev_b32_e32 v122, 16, v116
	v_and_b32_e32 v123, 0xffff0000, v116
	v_lshlrev_b32_e32 v116, 16, v117
	v_and_b32_e32 v117, 0xffff0000, v117
	v_lshlrev_b32_e32 v124, 16, v118
	v_and_b32_e32 v125, 0xffff0000, v118
	v_lshlrev_b32_e32 v118, 16, v119
	v_and_b32_e32 v119, 0xffff0000, v119
	v_pk_fma_f32 v[116:117], v[110:111], 0.5, v[116:117] op_sel_hi:[1,0,1]
	v_pk_fma_f32 v[122:123], v[108:109], 0.5, v[122:123] op_sel_hi:[1,0,1]
	v_pk_fma_f32 v[118:119], v[106:107], 0.5, v[118:119] op_sel_hi:[1,0,1]
	v_pk_fma_f32 v[124:125], v[104:105], 0.5, v[124:125] op_sel_hi:[1,0,1]
	v_cvt_pk_bf16_f32 v104, v122, v123
	v_cvt_pk_bf16_f32 v105, v116, v117
	v_mul_f32_e32 v123, v123, v123
	v_cvt_pk_bf16_f32 v106, v124, v125
	v_cvt_pk_bf16_f32 v107, v118, v119
	s_nop 1
	v_mov_b64_e32 v[108:109], v[176:177]
	v_mov_b64_e32 v[110:111], v[178:179]
	v_mul_f32_e32 v117, v117, v117
	v_mul_f32_e32 v125, v125, v125
	v_mul_f32_e32 v119, v119, v119
	v_fmac_f32_e32 v123, v122, v122
	v_fmac_f32_e32 v117, v116, v116
	v_fmac_f32_e32 v125, v124, v124
	v_fmac_f32_e32 v119, v118, v118
	v_add_f32_e32 v116, v123, v117
	v_add_f32_e32 v117, v125, v119
	v_add_f32_e32 v122, v116, v117
	global_store_dwordx4 v[120:121], v[104:107], off
	v_lshlrev_b32_e32 v116, 16, v108
	v_and_b32_e32 v117, 0xffff0000, v108
	v_lshlrev_b32_e32 v108, 16, v109
	v_and_b32_e32 v109, 0xffff0000, v109
	v_lshlrev_b32_e32 v118, 16, v110
	v_and_b32_e32 v119, 0xffff0000, v110
	v_lshlrev_b32_e32 v110, 16, v111
	v_and_b32_e32 v111, 0xffff0000, v111
	v_pk_fma_f32 v[102:103], v[102:103], 0.5, v[108:109] op_sel_hi:[1,0,1]
	v_pk_fma_f32 v[100:101], v[100:101], 0.5, v[116:117] op_sel_hi:[1,0,1]
	v_pk_fma_f32 v[108:109], v[98:99], 0.5, v[110:111] op_sel_hi:[1,0,1]
	v_pk_fma_f32 v[110:111], v[96:97], 0.5, v[118:119] op_sel_hi:[1,0,1]
	v_mul_f32_e32 v96, v101, v101
	v_mul_f32_e32 v97, v103, v103
	v_mul_f32_e32 v98, v111, v111
	v_mul_f32_e32 v99, v109, v109
	v_fmac_f32_e32 v96, v100, v100
	v_fmac_f32_e32 v97, v102, v102
	v_fmac_f32_e32 v98, v110, v110
	v_fmac_f32_e32 v99, v108, v108
	v_add_f32_e32 v96, v96, v97
	v_add_f32_e32 v97, v98, v99
	v_add_f32_e32 v96, v96, v97
	v_add_f32_e32 v96, v122, v96
	ds_bpermute_b32 v97, v114, v96
	v_cvt_pk_bf16_f32 v98, v100, v101
	v_cvt_pk_bf16_f32 v99, v102, v103
	v_cvt_pk_bf16_f32 v100, v110, v111
	v_cvt_pk_bf16_f32 v101, v108, v109
	s_waitcnt lgkmcnt(0)
	v_add_f32_e32 v96, v96, v97
	ds_bpermute_b32 v97, v115, v96
	global_store_dwordx4 v[120:121], v[98:101], off offset:256
	s_and_saveexec_b64 s[44:45], s[36:37]
	s_cbranch_execz .LBB0_912
	v_lshl_add_u64 v[98:99], v[112:113], 2, s[12:13]
	s_waitcnt lgkmcnt(0)
	v_add_f32_e32 v96, v96, v97
	global_atomic_add_f32 v[98:99], v96, off
.LBB0_912:
	s_or_b64 exec, exec, s[44:45]
	v_or_b32_e32 v96, 32, v146
	s_waitcnt lgkmcnt(0)
	v_ashrrev_i32_e32 v97, 31, v96
	v_lshlrev_b64 v[98:99], 11, v[96:97]
	v_lshl_add_u64 v[98:99], s[96:97], 0, v[98:99]
	v_lshl_add_u64 v[102:103], v[144:145], 1, v[98:99]
	s_nop 1
	v_mov_b64_e32 v[98:99], v[180:181]
	v_mov_b64_e32 v[100:101], v[182:183]
	v_lshlrev_b32_e32 v104, 16, v98
	v_and_b32_e32 v105, 0xffff0000, v98
	v_lshlrev_b32_e32 v98, 16, v99
	v_and_b32_e32 v99, 0xffff0000, v99
	v_lshlrev_b32_e32 v106, 16, v100
	v_and_b32_e32 v107, 0xffff0000, v100
	v_lshlrev_b32_e32 v100, 16, v101
	v_and_b32_e32 v101, 0xffff0000, v101
	v_pk_fma_f32 v[98:99], v[94:95], 0.5, v[98:99] op_sel_hi:[1,0,1]
	v_pk_fma_f32 v[104:105], v[92:93], 0.5, v[104:105] op_sel_hi:[1,0,1]
	v_pk_fma_f32 v[100:101], v[90:91], 0.5, v[100:101] op_sel_hi:[1,0,1]
	v_pk_fma_f32 v[106:107], v[88:89], 0.5, v[106:107] op_sel_hi:[1,0,1]
	v_cvt_pk_bf16_f32 v88, v104, v105
	v_cvt_pk_bf16_f32 v89, v98, v99
	v_mul_f32_e32 v105, v105, v105
	v_cvt_pk_bf16_f32 v90, v106, v107
	v_cvt_pk_bf16_f32 v91, v100, v101
	s_nop 1
	v_mov_b64_e32 v[92:93], v[184:185]
	v_mov_b64_e32 v[94:95], v[186:187]
	v_mul_f32_e32 v99, v99, v99
	v_mul_f32_e32 v107, v107, v107
	v_mul_f32_e32 v101, v101, v101
	v_fmac_f32_e32 v105, v104, v104
	v_fmac_f32_e32 v99, v98, v98
	v_fmac_f32_e32 v107, v106, v106
	v_fmac_f32_e32 v101, v100, v100
	v_add_f32_e32 v98, v105, v99
	v_add_f32_e32 v99, v107, v101
	v_add_f32_e32 v104, v98, v99
	global_store_dwordx4 v[102:103], v[88:91], off
	v_lshlrev_b32_e32 v98, 16, v92
	v_and_b32_e32 v99, 0xffff0000, v92
	v_lshlrev_b32_e32 v92, 16, v93
	v_and_b32_e32 v93, 0xffff0000, v93
	v_lshlrev_b32_e32 v100, 16, v94
	v_and_b32_e32 v101, 0xffff0000, v94
	v_lshlrev_b32_e32 v94, 16, v95
	v_and_b32_e32 v95, 0xffff0000, v95
	v_pk_fma_f32 v[86:87], v[86:87], 0.5, v[92:93] op_sel_hi:[1,0,1]
	v_pk_fma_f32 v[84:85], v[84:85], 0.5, v[98:99] op_sel_hi:[1,0,1]
	v_pk_fma_f32 v[92:93], v[82:83], 0.5, v[94:95] op_sel_hi:[1,0,1]
	v_pk_fma_f32 v[94:95], v[80:81], 0.5, v[100:101] op_sel_hi:[1,0,1]
	v_mul_f32_e32 v80, v85, v85
	v_mul_f32_e32 v81, v87, v87
	v_mul_f32_e32 v82, v95, v95
	v_mul_f32_e32 v83, v93, v93
	v_fmac_f32_e32 v80, v84, v84
	v_fmac_f32_e32 v81, v86, v86
	v_fmac_f32_e32 v82, v94, v94
	v_fmac_f32_e32 v83, v92, v92
	v_add_f32_e32 v80, v80, v81
	v_add_f32_e32 v81, v82, v83
	v_add_f32_e32 v80, v80, v81
	v_add_f32_e32 v80, v104, v80
	ds_bpermute_b32 v81, v114, v80
	v_cvt_pk_bf16_f32 v82, v84, v85
	v_cvt_pk_bf16_f32 v83, v86, v87
	v_cvt_pk_bf16_f32 v84, v94, v95
	v_cvt_pk_bf16_f32 v85, v92, v93
	s_waitcnt lgkmcnt(0)
	v_add_f32_e32 v80, v80, v81
	ds_bpermute_b32 v81, v115, v80
	global_store_dwordx4 v[102:103], v[82:85], off offset:256
	s_and_saveexec_b64 s[44:45], s[36:37]
	s_cbranch_execz .LBB0_914
	v_lshl_add_u64 v[82:83], v[96:97], 2, s[12:13]
	s_waitcnt lgkmcnt(0)
	v_add_f32_e32 v80, v80, v81
	global_atomic_add_f32 v[82:83], v80, off
; __device__ __forceinline__ float sq4(f32x4 a) { return (a.x * a.x + a.y * a.y) + (a.z * a.z + a.w * a.w); }
; __device__ __forceinline__ u32x4 pack8(f32x4 a, f32x4 b) { u32x4 o; o.x = cvt_pk(a.x, a.y); o.y = cvt_pk(a.z, a.w); o.z = cvt_pk(b.x, b.y); o.w = cvt_pk(b.z, b.w); return o; }
;     __device__ __forceinline__ void operator()(const f32x4 (&acc)[2][2][4][2], const pg8::Unit& u, int wr, int wc, int fr, int fq) const {
;     ...
; #pragma unroll
;         for (int ai = 0; ai < 2; ++ai)
; #pragma unroll
;             for (int m = 0; m < 4; ++m) {
;                 const int row = row0 + ai * 128 + m * 16; float ssq = 0.f;
; #pragma unroll
;                 for (int bj = 0; bj < 2; ++bj) {
;                     const size_t idx = (size_t)row * D + col0 + bj * 128;
;                     f32x4 r0, r1;
;                     if (RF32) { r0 = *(const f32x4*)(R + idx); r1 = *(const f32x4*)(R + idx + 4); }
;                     else { const u32x4 w = *(const u32x4*)(X + idx); r0 = (f32x4){bflo(w.x), bfhi(w.x), bflo(w.y), bfhi(w.y)}; r1 = (f32x4){bflo(w.z), bfhi(w.z), bflo(w.w), bfhi(w.w)}; }
;                     const f32x4 v0 = r0 + acc[ai][bj][m][0] * s, v1 = r1 + acc[ai][bj][m][1] * s;
;                     ssq += sq4(v0) + sq4(v1);
;                     *(u32x4*)(X + idx) = pack8(v0, v1);
;                 }
;                 row_stat_add(SS, row, ssq, fq);
;             }
.LBB0_914:
	s_or_b64 exec, exec, s[44:45]
	v_or_b32_e32 v80, 48, v146
	s_waitcnt lgkmcnt(0)
	v_ashrrev_i32_e32 v81, 31, v80
	v_lshlrev_b64 v[82:83], 11, v[80:81]
	v_lshl_add_u64 v[82:83], s[96:97], 0, v[82:83]
	v_lshl_add_u64 v[86:87], v[144:145], 1, v[82:83]
	s_nop 1
	v_mov_b64_e32 v[82:83], v[188:189]
	v_mov_b64_e32 v[84:85], v[190:191]
	v_lshlrev_b32_e32 v88, 16, v82
	v_and_b32_e32 v89, 0xffff0000, v82
	v_lshlrev_b32_e32 v82, 16, v83
	v_and_b32_e32 v83, 0xffff0000, v83
	v_lshlrev_b32_e32 v90, 16, v84
	v_and_b32_e32 v91, 0xffff0000, v84
	v_lshlrev_b32_e32 v84, 16, v85
	v_and_b32_e32 v85, 0xffff0000, v85
	v_pk_fma_f32 v[82:83], v[78:79], 0.5, v[82:83] op_sel_hi:[1,0,1]
	v_pk_fma_f32 v[88:89], v[76:77], 0.5, v[88:89] op_sel_hi:[1,0,1]
	v_pk_fma_f32 v[84:85], v[74:75], 0.5, v[84:85] op_sel_hi:[1,0,1]
	v_pk_fma_f32 v[90:91], v[72:73], 0.5, v[90:91] op_sel_hi:[1,0,1]
	v_cvt_pk_bf16_f32 v72, v88, v89
	v_cvt_pk_bf16_f32 v73, v82, v83
	v_mul_f32_e32 v89, v89, v89
	v_cvt_pk_bf16_f32 v74, v90, v91
	v_cvt_pk_bf16_f32 v75, v84, v85
	s_nop 1
	v_mov_b64_e32 v[76:77], v[192:193]
	v_mov_b64_e32 v[78:79], v[194:195]
	v_mul_f32_e32 v83, v83, v83
	v_mul_f32_e32 v91, v91, v91
	v_mul_f32_e32 v85, v85, v85
	v_fmac_f32_e32 v89, v88, v88
	v_fmac_f32_e32 v83, v82, v82
	v_fmac_f32_e32 v91, v90, v90
	v_fmac_f32_e32 v85, v84, v84
	v_add_f32_e32 v82, v89, v83
	v_add_f32_e32 v83, v91, v85
	v_add_f32_e32 v88, v82, v83
	global_store_dwordx4 v[86:87], v[72:75], off
	v_lshlrev_b32_e32 v82, 16, v76
	v_and_b32_e32 v83, 0xffff0000, v76
	v_lshlrev_b32_e32 v76, 16, v77
	v_and_b32_e32 v77, 0xffff0000, v77
	v_lshlrev_b32_e32 v84, 16, v78
	v_and_b32_e32 v85, 0xffff0000, v78
	v_lshlrev_b32_e32 v78, 16, v79
	v_and_b32_e32 v79, 0xffff0000, v79
	v_pk_fma_f32 v[70:71], v[70:71], 0.5, v[76:77] op_sel_hi:[1,0,1]
	v_pk_fma_f32 v[68:69], v[68:69], 0.5, v[82:83] op_sel_hi:[1,0,1]
	v_pk_fma_f32 v[76:77], v[66:67], 0.5, v[78:79] op_sel_hi:[1,0,1]
	v_pk_fma_f32 v[78:79], v[64:65], 0.5, v[84:85] op_sel_hi:[1,0,1]
	v_mul_f32_e32 v64, v69, v69
	v_mul_f32_e32 v65, v71, v71
	v_mul_f32_e32 v66, v79, v79
	v_mul_f32_e32 v67, v77, v77
	v_fmac_f32_e32 v64, v68, v68
	v_fmac_f32_e32 v65, v70, v70
	v_fmac_f32_e32 v66, v78, v78
	v_fmac_f32_e32 v67, v76, v76
	v_add_f32_e32 v64, v64, v65
	v_add_f32_e32 v65, v66, v67
	v_add_f32_e32 v64, v64, v65
	v_add_f32_e32 v64, v88, v64
	ds_bpermute_b32 v65, v114, v64
	v_cvt_pk_bf16_f32 v66, v68, v69
	v_cvt_pk_bf16_f32 v67, v70, v71
	v_cvt_pk_bf16_f32 v68, v78, v79
	v_cvt_pk_bf16_f32 v69, v76, v77
	s_waitcnt lgkmcnt(0)
	v_add_f32_e32 v64, v64, v65
	ds_bpermute_b32 v65, v115, v64
	global_store_dwordx4 v[86:87], v[66:69], off offset:256
	s_and_saveexec_b64 s[44:45], s[36:37]
	s_cbranch_execz .LBB0_916
	v_lshl_add_u64 v[66:67], v[80:81], 2, s[12:13]
	s_waitcnt lgkmcnt(0)
	v_add_f32_e32 v64, v64, v65
	global_atomic_add_f32 v[66:67], v64, off
.LBB0_916:
	s_or_b64 exec, exec, s[44:45]
	v_add_u32_e32 v64, 0x80, v146
	s_waitcnt lgkmcnt(0)
	v_ashrrev_i32_e32 v65, 31, v64
	v_lshlrev_b64 v[66:67], 11, v[64:65]
	v_lshl_add_u64 v[66:67], s[96:97], 0, v[66:67]
	v_lshl_add_u64 v[70:71], v[144:145], 1, v[66:67]
	s_nop 1
	v_mov_b64_e32 v[66:67], v[196:197]
	v_mov_b64_e32 v[68:69], v[198:199]
	v_lshlrev_b32_e32 v72, 16, v66
	v_and_b32_e32 v73, 0xffff0000, v66
	v_lshlrev_b32_e32 v66, 16, v67
	v_and_b32_e32 v67, 0xffff0000, v67
	v_lshlrev_b32_e32 v74, 16, v68
	v_and_b32_e32 v75, 0xffff0000, v68
	v_lshlrev_b32_e32 v68, 16, v69
	v_and_b32_e32 v69, 0xffff0000, v69
	v_pk_fma_f32 v[66:67], v[62:63], 0.5, v[66:67] op_sel_hi:[1,0,1]
	v_pk_fma_f32 v[72:73], v[60:61], 0.5, v[72:73] op_sel_hi:[1,0,1]
	v_pk_fma_f32 v[68:69], v[58:59], 0.5, v[68:69] op_sel_hi:[1,0,1]
	v_pk_fma_f32 v[74:75], v[56:57], 0.5, v[74:75] op_sel_hi:[1,0,1]
	v_cvt_pk_bf16_f32 v56, v72, v73
	v_cvt_pk_bf16_f32 v57, v66, v67
	v_mul_f32_e32 v73, v73, v73
	v_cvt_pk_bf16_f32 v58, v74, v75
	v_cvt_pk_bf16_f32 v59, v68, v69
	s_nop 1
	v_mov_b64_e32 v[60:61], v[200:201]
	v_mov_b64_e32 v[62:63], v[202:203]
	v_mul_f32_e32 v67, v67, v67
	v_mul_f32_e32 v75, v75, v75
	v_mul_f32_e32 v69, v69, v69
	v_fmac_f32_e32 v73, v72, v72
	v_fmac_f32_e32 v67, v66, v66
	v_fmac_f32_e32 v75, v74, v74
	v_fmac_f32_e32 v69, v68, v68
	v_add_f32_e32 v66, v73, v67
	v_add_f32_e32 v67, v75, v69
	v_add_f32_e32 v72, v66, v67
	global_store_dwordx4 v[70:71], v[56:59], off
	v_lshlrev_b32_e32 v66, 16, v60
	v_and_b32_e32 v67, 0xffff0000, v60
	v_lshlrev_b32_e32 v60, 16, v61
	v_and_b32_e32 v61, 0xffff0000, v61
	v_lshlrev_b32_e32 v68, 16, v62
	v_and_b32_e32 v69, 0xffff0000, v62
	v_lshlrev_b32_e32 v62, 16, v63
	v_and_b32_e32 v63, 0xffff0000, v63
	v_pk_fma_f32 v[54:55], v[54:55], 0.5, v[60:61] op_sel_hi:[1,0,1]
	v_pk_fma_f32 v[52:53], v[52:53], 0.5, v[66:67] op_sel_hi:[1,0,1]
	v_pk_fma_f32 v[60:61], v[50:51], 0.5, v[62:63] op_sel_hi:[1,0,1]
	v_pk_fma_f32 v[62:63], v[48:49], 0.5, v[68:69] op_sel_hi:[1,0,1]
	v_mul_f32_e32 v48, v53, v53
	v_mul_f32_e32 v49, v55, v55
	v_mul_f32_e32 v50, v63, v63
	v_mul_f32_e32 v51, v61, v61
	v_fmac_f32_e32 v48, v52, v52
	v_fmac_f32_e32 v49, v54, v54
	v_fmac_f32_e32 v50, v62, v62
	v_fmac_f32_e32 v51, v60, v60
	v_add_f32_e32 v48, v48, v49
	v_add_f32_e32 v49, v50, v51
	v_add_f32_e32 v48, v48, v49
	v_add_f32_e32 v48, v72, v48
	ds_bpermute_b32 v49, v114, v48
	v_cvt_pk_bf16_f32 v50, v52, v53
	v_cvt_pk_bf16_f32 v51, v54, v55
	v_cvt_pk_bf16_f32 v52, v62, v63
	v_cvt_pk_bf16_f32 v53, v60, v61
	s_waitcnt lgkmcnt(0)
	v_add_f32_e32 v48, v48, v49
	ds_bpermute_b32 v49, v115, v48
	global_store_dwordx4 v[70:71], v[50:53], off offset:256
	s_and_saveexec_b64 s[44:45], s[36:37]
	s_cbranch_execz .LBB0_918
	v_lshl_add_u64 v[50:51], v[64:65], 2, s[12:13]
	s_waitcnt lgkmcnt(0)
	v_add_f32_e32 v48, v48, v49
	global_atomic_add_f32 v[50:51], v48, off
; __device__ __forceinline__ float sq4(f32x4 a) { return (a.x * a.x + a.y * a.y) + (a.z * a.z + a.w * a.w); }
; __device__ __forceinline__ u32x4 pack8(f32x4 a, f32x4 b) { u32x4 o; o.x = cvt_pk(a.x, a.y); o.y = cvt_pk(a.z, a.w); o.z = cvt_pk(b.x, b.y); o.w = cvt_pk(b.z, b.w); return o; }
;     __device__ __forceinline__ void operator()(const f32x4 (&acc)[2][2][4][2], const pg8::Unit& u, int wr, int wc, int fr, int fq) const {
;     ...
; #pragma unroll
;         for (int ai = 0; ai < 2; ++ai)
; #pragma unroll
;             for (int m = 0; m < 4; ++m) {
;                 const int row = row0 + ai * 128 + m * 16; float ssq = 0.f;
; #pragma unroll
;                 for (int bj = 0; bj < 2; ++bj) {
;                     const size_t idx = (size_t)row * D + col0 + bj * 128;
;                     f32x4 r0, r1;
;                     if (RF32) { r0 = *(const f32x4*)(R + idx); r1 = *(const f32x4*)(R + idx + 4); }
;                     else { const u32x4 w = *(const u32x4*)(X + idx); r0 = (f32x4){bflo(w.x), bfhi(w.x), bflo(w.y), bfhi(w.y)}; r1 = (f32x4){bflo(w.z), bfhi(w.z), bflo(w.w), bfhi(w.w)}; }
;                     const f32x4 v0 = r0 + acc[ai][bj][m][0] * s, v1 = r1 + acc[ai][bj][m][1] * s;
;                     ssq += sq4(v0) + sq4(v1);
;                     *(u32x4*)(X + idx) = pack8(v0, v1);
;                 }
;                 row_stat_add(SS, row, ssq, fq);
;             }
.LBB0_918:
	s_or_b64 exec, exec, s[44:45]
	v_add_u32_e32 v48, 0x90, v146
	s_waitcnt lgkmcnt(0)
	v_ashrrev_i32_e32 v49, 31, v48
	v_lshlrev_b64 v[50:51], 11, v[48:49]
	v_lshl_add_u64 v[50:51], s[96:97], 0, v[50:51]
	v_lshl_add_u64 v[54:55], v[144:145], 1, v[50:51]
	s_nop 1
	v_mov_b64_e32 v[50:51], v[204:205]
	v_mov_b64_e32 v[52:53], v[206:207]
	v_lshlrev_b32_e32 v56, 16, v50
	v_and_b32_e32 v57, 0xffff0000, v50
	v_lshlrev_b32_e32 v50, 16, v51
	v_and_b32_e32 v51, 0xffff0000, v51
	v_lshlrev_b32_e32 v58, 16, v52
	v_and_b32_e32 v59, 0xffff0000, v52
	v_lshlrev_b32_e32 v52, 16, v53
	v_and_b32_e32 v53, 0xffff0000, v53
	v_pk_fma_f32 v[50:51], v[46:47], 0.5, v[50:51] op_sel_hi:[1,0,1]
	v_pk_fma_f32 v[56:57], v[44:45], 0.5, v[56:57] op_sel_hi:[1,0,1]
	v_pk_fma_f32 v[52:53], v[42:43], 0.5, v[52:53] op_sel_hi:[1,0,1]
	v_pk_fma_f32 v[58:59], v[40:41], 0.5, v[58:59] op_sel_hi:[1,0,1]
	v_cvt_pk_bf16_f32 v40, v56, v57
	v_cvt_pk_bf16_f32 v41, v50, v51
	v_mul_f32_e32 v57, v57, v57
	v_cvt_pk_bf16_f32 v42, v58, v59
	v_cvt_pk_bf16_f32 v43, v52, v53
	s_nop 1
	v_mov_b64_e32 v[44:45], v[208:209]
	v_mov_b64_e32 v[46:47], v[210:211]
	v_mul_f32_e32 v51, v51, v51
	v_mul_f32_e32 v59, v59, v59
	v_mul_f32_e32 v53, v53, v53
	v_fmac_f32_e32 v57, v56, v56
	v_fmac_f32_e32 v51, v50, v50
	v_fmac_f32_e32 v59, v58, v58
	v_fmac_f32_e32 v53, v52, v52
	v_add_f32_e32 v50, v57, v51
	v_add_f32_e32 v51, v59, v53
	v_add_f32_e32 v56, v50, v51
	global_store_dwordx4 v[54:55], v[40:43], off
	v_lshlrev_b32_e32 v50, 16, v44
	v_and_b32_e32 v51, 0xffff0000, v44
	v_lshlrev_b32_e32 v44, 16, v45
	v_and_b32_e32 v45, 0xffff0000, v45
	v_lshlrev_b32_e32 v52, 16, v46
	v_and_b32_e32 v53, 0xffff0000, v46
	v_lshlrev_b32_e32 v46, 16, v47
	v_and_b32_e32 v47, 0xffff0000, v47
	v_pk_fma_f32 v[38:39], v[38:39], 0.5, v[44:45] op_sel_hi:[1,0,1]
	v_pk_fma_f32 v[36:37], v[36:37], 0.5, v[50:51] op_sel_hi:[1,0,1]
	v_pk_fma_f32 v[44:45], v[34:35], 0.5, v[46:47] op_sel_hi:[1,0,1]
	v_pk_fma_f32 v[46:47], v[32:33], 0.5, v[52:53] op_sel_hi:[1,0,1]
	v_mul_f32_e32 v32, v37, v37
	v_mul_f32_e32 v33, v39, v39
	v_mul_f32_e32 v34, v47, v47
	v_mul_f32_e32 v35, v45, v45
	v_fmac_f32_e32 v32, v36, v36
	v_fmac_f32_e32 v33, v38, v38
	v_fmac_f32_e32 v34, v46, v46
	v_fmac_f32_e32 v35, v44, v44
	v_add_f32_e32 v32, v32, v33
	v_add_f32_e32 v33, v34, v35
	v_add_f32_e32 v32, v32, v33
	v_add_f32_e32 v32, v56, v32
	ds_bpermute_b32 v33, v114, v32
	v_cvt_pk_bf16_f32 v34, v36, v37
	v_cvt_pk_bf16_f32 v35, v38, v39
	v_cvt_pk_bf16_f32 v36, v46, v47
	v_cvt_pk_bf16_f32 v37, v44, v45
	s_waitcnt lgkmcnt(0)
	v_add_f32_e32 v32, v32, v33
	ds_bpermute_b32 v33, v115, v32
	global_store_dwordx4 v[54:55], v[34:37], off offset:256
	s_and_saveexec_b64 s[44:45], s[36:37]
	s_cbranch_execz .LBB0_920
	v_lshl_add_u64 v[34:35], v[48:49], 2, s[12:13]
	s_waitcnt lgkmcnt(0)
	v_add_f32_e32 v32, v32, v33
	global_atomic_add_f32 v[34:35], v32, off
; __device__ __forceinline__ float sq4(f32x4 a) { return (a.x * a.x + a.y * a.y) + (a.z * a.z + a.w * a.w); }
; __device__ __forceinline__ u32x4 pack8(f32x4 a, f32x4 b) { u32x4 o; o.x = cvt_pk(a.x, a.y); o.y = cvt_pk(a.z, a.w); o.z = cvt_pk(b.x, b.y); o.w = cvt_pk(b.z, b.w); return o; }
;     __device__ __forceinline__ void operator()(const f32x4 (&acc)[2][2][4][2], const pg8::Unit& u, int wr, int wc, int fr, int fq) const {
;     ...
; #pragma unroll
;         for (int ai = 0; ai < 2; ++ai)
; #pragma unroll
;             for (int m = 0; m < 4; ++m) {
;                 const int row = row0 + ai * 128 + m * 16; float ssq = 0.f;
; #pragma unroll
;                 for (int bj = 0; bj < 2; ++bj) {
;                     const size_t idx = (size_t)row * D + col0 + bj * 128;
;                     f32x4 r0, r1;
;                     if (RF32) { r0 = *(const f32x4*)(R + idx); r1 = *(const f32x4*)(R + idx + 4); }
;                     else { const u32x4 w = *(const u32x4*)(X + idx); r0 = (f32x4){bflo(w.x), bfhi(w.x), bflo(w.y), bfhi(w.y)}; r1 = (f32x4){bflo(w.z), bfhi(w.z), bflo(w.w), bfhi(w.w)}; }
;                     const f32x4 v0 = r0 + acc[ai][bj][m][0] * s, v1 = r1 + acc[ai][bj][m][1] * s;
;                     ssq += sq4(v0) + sq4(v1);
;                     *(u32x4*)(X + idx) = pack8(v0, v1);
;                 }
;                 row_stat_add(SS, row, ssq, fq);
;             }
.LBB0_920:
	s_or_b64 exec, exec, s[44:45]
	v_add_u32_e32 v32, 0xa0, v146
	s_waitcnt lgkmcnt(0)
	v_ashrrev_i32_e32 v33, 31, v32
	v_lshlrev_b64 v[34:35], 11, v[32:33]
	v_lshl_add_u64 v[34:35], s[96:97], 0, v[34:35]
	v_lshl_add_u64 v[38:39], v[144:145], 1, v[34:35]
	s_nop 1
	v_mov_b64_e32 v[34:35], v[212:213]
	v_mov_b64_e32 v[36:37], v[214:215]
	v_lshlrev_b32_e32 v40, 16, v34
	v_and_b32_e32 v41, 0xffff0000, v34
	v_lshlrev_b32_e32 v34, 16, v35
	v_and_b32_e32 v35, 0xffff0000, v35
	v_lshlrev_b32_e32 v42, 16, v36
	v_and_b32_e32 v43, 0xffff0000, v36
	v_lshlrev_b32_e32 v36, 16, v37
	v_and_b32_e32 v37, 0xffff0000, v37
	v_pk_fma_f32 v[34:35], v[30:31], 0.5, v[34:35] op_sel_hi:[1,0,1]
	v_pk_fma_f32 v[40:41], v[28:29], 0.5, v[40:41] op_sel_hi:[1,0,1]
	v_pk_fma_f32 v[36:37], v[26:27], 0.5, v[36:37] op_sel_hi:[1,0,1]
	v_pk_fma_f32 v[42:43], v[24:25], 0.5, v[42:43] op_sel_hi:[1,0,1]
	v_cvt_pk_bf16_f32 v24, v40, v41
	v_cvt_pk_bf16_f32 v25, v34, v35
	v_mul_f32_e32 v41, v41, v41
	v_cvt_pk_bf16_f32 v26, v42, v43
	v_cvt_pk_bf16_f32 v27, v36, v37
	s_nop 1
	v_mov_b64_e32 v[28:29], v[216:217]
	v_mov_b64_e32 v[30:31], v[218:219]
	v_mul_f32_e32 v35, v35, v35
	v_mul_f32_e32 v43, v43, v43
	v_mul_f32_e32 v37, v37, v37
	v_fmac_f32_e32 v41, v40, v40
	v_fmac_f32_e32 v35, v34, v34
	v_fmac_f32_e32 v43, v42, v42
	v_fmac_f32_e32 v37, v36, v36
	v_add_f32_e32 v34, v41, v35
	v_add_f32_e32 v35, v43, v37
	v_add_f32_e32 v40, v34, v35
	global_store_dwordx4 v[38:39], v[24:27], off
	v_lshlrev_b32_e32 v34, 16, v28
	v_and_b32_e32 v35, 0xffff0000, v28
	v_lshlrev_b32_e32 v28, 16, v29
	v_and_b32_e32 v29, 0xffff0000, v29
	v_lshlrev_b32_e32 v36, 16, v30
	v_and_b32_e32 v37, 0xffff0000, v30
	v_lshlrev_b32_e32 v30, 16, v31
	v_and_b32_e32 v31, 0xffff0000, v31
	v_pk_fma_f32 v[22:23], v[22:23], 0.5, v[28:29] op_sel_hi:[1,0,1]
	v_pk_fma_f32 v[20:21], v[20:21], 0.5, v[34:35] op_sel_hi:[1,0,1]
	v_pk_fma_f32 v[28:29], v[18:19], 0.5, v[30:31] op_sel_hi:[1,0,1]
	v_pk_fma_f32 v[30:31], v[16:17], 0.5, v[36:37] op_sel_hi:[1,0,1]
	v_mul_f32_e32 v16, v21, v21
	v_mul_f32_e32 v17, v23, v23
	v_mul_f32_e32 v18, v31, v31
	v_mul_f32_e32 v19, v29, v29
	v_fmac_f32_e32 v16, v20, v20
	v_fmac_f32_e32 v17, v22, v22
	v_fmac_f32_e32 v18, v30, v30
	v_fmac_f32_e32 v19, v28, v28
	v_add_f32_e32 v16, v16, v17
	v_add_f32_e32 v17, v18, v19
	v_add_f32_e32 v16, v16, v17
	v_add_f32_e32 v16, v40, v16
	ds_bpermute_b32 v17, v114, v16
	v_cvt_pk_bf16_f32 v18, v20, v21
	v_cvt_pk_bf16_f32 v19, v22, v23
	v_cvt_pk_bf16_f32 v20, v30, v31
	v_cvt_pk_bf16_f32 v21, v28, v29
	s_waitcnt lgkmcnt(0)
	v_add_f32_e32 v16, v16, v17
	ds_bpermute_b32 v17, v115, v16
	global_store_dwordx4 v[38:39], v[18:21], off offset:256
	s_and_saveexec_b64 s[44:45], s[36:37]
	s_cbranch_execz .LBB0_922
	v_lshl_add_u64 v[18:19], v[32:33], 2, s[12:13]
	s_waitcnt lgkmcnt(0)
	v_add_f32_e32 v16, v16, v17
	global_atomic_add_f32 v[18:19], v16, off
.LBB0_922:
	s_or_b64 exec, exec, s[44:45]
	v_add_u32_e32 v16, 0xb0, v146
	s_waitcnt lgkmcnt(0)
	v_ashrrev_i32_e32 v17, 31, v16
	v_lshlrev_b64 v[18:19], 11, v[16:17]
	v_lshl_add_u64 v[18:19], s[96:97], 0, v[18:19]
	v_lshl_add_u64 v[22:23], v[144:145], 1, v[18:19]
	s_nop 1
	v_mov_b64_e32 v[18:19], v[220:221]
	v_mov_b64_e32 v[20:21], v[222:223]
	v_lshlrev_b32_e32 v24, 16, v18
	v_and_b32_e32 v25, 0xffff0000, v18
	v_lshlrev_b32_e32 v18, 16, v19
	v_and_b32_e32 v19, 0xffff0000, v19
	v_lshlrev_b32_e32 v26, 16, v20
	v_and_b32_e32 v27, 0xffff0000, v20
	v_lshlrev_b32_e32 v20, 16, v21
	v_and_b32_e32 v21, 0xffff0000, v21
	v_pk_fma_f32 v[18:19], v[14:15], 0.5, v[18:19] op_sel_hi:[1,0,1]
	v_pk_fma_f32 v[24:25], v[12:13], 0.5, v[24:25] op_sel_hi:[1,0,1]
	v_pk_fma_f32 v[20:21], v[10:11], 0.5, v[20:21] op_sel_hi:[1,0,1]
	v_pk_fma_f32 v[26:27], v[8:9], 0.5, v[26:27] op_sel_hi:[1,0,1]
	v_cvt_pk_bf16_f32 v8, v24, v25
	v_cvt_pk_bf16_f32 v9, v18, v19
	v_mul_f32_e32 v25, v25, v25
	v_cvt_pk_bf16_f32 v10, v26, v27
	v_cvt_pk_bf16_f32 v11, v20, v21
	global_load_dwordx4 v[12:15], v[22:23], off offset:256
	v_mul_f32_e32 v19, v19, v19
	v_mul_f32_e32 v27, v27, v27
	v_mul_f32_e32 v21, v21, v21
	v_fmac_f32_e32 v25, v24, v24
	v_fmac_f32_e32 v19, v18, v18
	v_fmac_f32_e32 v27, v26, v26
	v_fmac_f32_e32 v21, v20, v20
	v_add_f32_e32 v18, v25, v19
	v_add_f32_e32 v19, v27, v21
	v_add_f32_e32 v24, v18, v19
	global_store_dwordx4 v[22:23], v[8:11], off
	s_waitcnt vmcnt(1)
	v_lshlrev_b32_e32 v18, 16, v12
	v_and_b32_e32 v19, 0xffff0000, v12
	v_lshlrev_b32_e32 v12, 16, v13
	v_and_b32_e32 v13, 0xffff0000, v13
	v_lshlrev_b32_e32 v20, 16, v14
	v_and_b32_e32 v21, 0xffff0000, v14
	v_lshlrev_b32_e32 v14, 16, v15
	v_and_b32_e32 v15, 0xffff0000, v15
	v_pk_fma_f32 v[6:7], v[6:7], 0.5, v[12:13] op_sel_hi:[1,0,1]
	v_pk_fma_f32 v[4:5], v[4:5], 0.5, v[18:19] op_sel_hi:[1,0,1]
	v_pk_fma_f32 v[12:13], v[2:3], 0.5, v[14:15] op_sel_hi:[1,0,1]
	v_pk_fma_f32 v[14:15], v[0:1], 0.5, v[20:21] op_sel_hi:[1,0,1]
	v_mul_f32_e32 v0, v5, v5
	v_mul_f32_e32 v1, v7, v7
	v_mul_f32_e32 v2, v15, v15
	v_mul_f32_e32 v3, v13, v13
	v_fmac_f32_e32 v0, v4, v4
	v_fmac_f32_e32 v1, v6, v6
	v_fmac_f32_e32 v2, v14, v14
	v_fmac_f32_e32 v3, v12, v12
	v_add_f32_e32 v0, v0, v1
	v_add_f32_e32 v1, v2, v3
	v_add_f32_e32 v0, v0, v1
	v_add_f32_e32 v0, v24, v0
	ds_bpermute_b32 v1, v114, v0
	v_cvt_pk_bf16_f32 v2, v4, v5
	v_cvt_pk_bf16_f32 v3, v6, v7
	v_cvt_pk_bf16_f32 v4, v14, v15
	v_cvt_pk_bf16_f32 v5, v12, v13
	s_waitcnt lgkmcnt(0)
	v_add_f32_e32 v0, v0, v1
	ds_bpermute_b32 v1, v115, v0
	global_store_dwordx4 v[22:23], v[2:5], off offset:256
	s_and_saveexec_b64 s[44:45], s[36:37]
	s_cbranch_execz .LBB0_924
	v_lshl_add_u64 v[2:3], v[16:17], 2, s[12:13]
	s_waitcnt lgkmcnt(0)
	v_add_f32_e32 v0, v0, v1
	global_atomic_add_f32 v[2:3], v0, off
